# chunk scan: each wave computes the 64 per-token rstd itself (lane = token) and distributes them with ds_bpermute; the RL array and one of the three workgroup barriers per chunk are gone
# baseline (speedup 1.0000x reference)
.LBB0_1038:
	s_and_b64 vcc, exec, s[0:1]
	s_cbranch_vccz .LBB0_1083
	s_lshl_b32 s0, s84, 8
	s_and_b32 s14, s0, 0xfffff800
	s_lshl_b32 s8, s84, 5
	s_ashr_i32 s15, s14, 31
	s_mov_b64 s[38:39], s[28:29]
	s_and_b32 s28, s0, 0x700
	s_add_u32 s30, s68, s28
	s_addc_u32 s31, s69, 0
	s_add_u32 s34, s3, s28
	s_addc_u32 s35, s85, 0
	s_ashr_i32 s9, s8, 31
	s_lshl_b64 s[2:3], s[8:9], 14
	s_add_u32 s36, s38, s2
	s_addc_u32 s37, s39, s3
	s_add_u32 s10, s92, s28
	s_addc_u32 s11, s93, 0
	s_lshl_b64 s[0:1], s[8:9], 13
	s_add_u32 s0, s26, s0
	s_addc_u32 s1, s27, s1
	s_add_u32 s24, s66, s2
	s_addc_u32 s25, s67, s3
	s_lshl_b64 s[12:13], s[8:9], 2
	s_add_u32 s22, s78, s12
	s_addc_u32 s23, s79, s13
	s_or_b32 s2, s8, 1
	s_or_b32 s6, s14, 64
	s_ashr_i32 s3, s2, 31
	s_ashr_i32 s7, s6, 31
	s_lshl_b64 s[4:5], s[2:3], 14
	s_add_u32 s20, s38, s4
	s_addc_u32 s21, s39, s5
	s_lshl_b64 s[16:17], s[2:3], 13
	s_add_u32 s16, s26, s16
	s_addc_u32 s17, s27, s17
	s_add_u32 s18, s66, s4
	s_addc_u32 s19, s67, s5
	s_lshl_b64 s[2:3], s[2:3], 2
	s_add_u32 s4, s78, s2
	s_waitcnt vmcnt(10)
	v_mov_b32_e32 v46, v0
	v_readfirstlane_b32 s2, v0
	s_addc_u32 s5, s79, s3
	s_lshr_b32 s9, s2, 6
	v_lshlrev_b32_e32 v10, 3, v46
	v_ashrrev_i32_e32 v108, 4, v46
	v_and_b32_e32 v1, 15, v46
	s_lshl_b32 s2, s9, 4
	v_and_b32_e32 v47, 0x78, v10
	v_ashrrev_i32_e32 v109, 31, v108
	v_mov_b32_e32 v103, 0
	v_or_b32_e32 v2, s2, v1
	v_readlane_b32 s40, v245, 26
	v_lshlrev_b32_e32 v102, 1, v47
	v_lshl_add_u64 v[32:33], v[108:109], 0, s[14:15]
	s_waitcnt vmcnt(7)
	v_add_u32_e32 v49, 0x200, v46
	v_lshlrev_b32_e32 v2, 2, v2
	v_readlane_b32 s48, v245, 34
	v_readlane_b32 s49, v245, 35
	v_lshl_add_u64 v[104:105], s[30:31], 0, v[102:103]
	v_lshl_add_u64 v[106:107], s[34:35], 0, v[102:103]
	v_lshlrev_b64 v[34:35], 11, v[32:33]
	v_ashrrev_i32_e32 v112, 4, v49
	v_and_b32_e32 v48, 56, v10
	global_load_dword v128, v2, s[48:49]
	v_lshl_add_u64 v[2:3], v[104:105], 0, v[34:35]
	v_lshl_add_u64 v[6:7], v[106:107], 0, v[34:35]
	v_and_b32_e32 v110, 0xffffffc0, v10
	v_ashrrev_i32_e32 v113, 31, v112
	s_barrier
	v_lshlrev_b32_e32 v30, 1, v48
	v_mov_b32_e32 v31, v103
	global_load_dwordx4 v[2:5], v[2:3], off nt
	s_nop 0
	global_load_dwordx4 v[6:9], v[6:7], off nt
	v_ashrrev_i32_e32 v111, 31, v110
	v_lshl_add_u64 v[38:39], v[112:113], 0, s[14:15]
	v_lshl_add_u64 v[22:23], s[36:37], 0, v[30:31]
	v_lshlrev_b64 v[36:37], 1, v[110:111]
	v_lshlrev_b64 v[40:41], 11, v[38:39]
	v_lshl_add_u64 v[10:11], v[22:23], 0, v[36:37]
	v_lshl_add_u64 v[14:15], v[104:105], 0, v[40:41]
	v_lshl_add_u64 v[18:19], v[106:107], 0, v[40:41]
	v_lshlrev_b32_e32 v24, 3, v49
	v_ashrrev_i32_e32 v50, 3, v46
	global_load_dwordx4 v[10:13], v[10:11], off nt
	s_nop 0
	global_load_dwordx4 v[14:17], v[14:15], off nt
	s_nop 0
	global_load_dwordx4 v[18:21], v[18:19], off nt
	v_and_b32_e32 v114, 0xffffffc0, v24
	v_lshlrev_b32_e32 v26, 6, v50
	v_ashrrev_i32_e32 v115, 31, v114
	v_ashrrev_i32_e32 v27, 31, v26
	v_lshlrev_b64 v[42:43], 1, v[114:115]
	v_lshlrev_b64 v[44:45], 1, v[26:27]
	v_lshl_add_u64 v[22:23], v[22:23], 0, v[42:43]
	v_lshl_add_u64 v[26:27], s[0:1], 0, v[44:45]
	global_load_dwordx4 v[22:25], v[22:23], off nt
	v_lshl_add_u64 v[26:27], v[26:27], 0, v[30:31]
	global_load_dwordx4 v[26:29], v[26:27], off nt
	v_lshl_add_u64 v[116:117], s[10:11], 0, v[102:103]
	v_lshl_add_u64 v[34:35], v[116:117], 0, v[34:35]
	v_and_b32_e32 v51, 63, v46
	global_load_dwordx4 v[66:69], v[34:35], off nt
	v_lshl_add_u64 v[34:35], v[116:117], 0, v[40:41]
	s_lshl_b32 s10, s9, 9
	global_load_dwordx4 v[62:65], v[34:35], off nt
	v_lshlrev_b32_e32 v34, 2, v51
	v_mov_b32_e32 v35, v103
	s_ashr_i32 s11, s10, 31
	v_lshl_add_u64 v[40:41], s[24:25], 0, v[34:35]
	s_lshl_b64 s[24:25], s[10:11], 2
	v_lshl_add_u64 v[40:41], v[40:41], 0, s[24:25]
	s_movk_i32 s0, 0x88
	global_load_dword v156, v[40:41], off nt
	global_load_dword v157, v[40:41], off offset:256 nt
	global_load_dword v145, v[40:41], off offset:512 nt
	global_load_dword v147, v[40:41], off offset:768 nt
	global_load_dword v152, v[40:41], off offset:1024 nt
	global_load_dword v153, v[40:41], off offset:1280 nt
	global_load_dword v154, v[40:41], off offset:1536 nt
	global_load_dword v155, v[40:41], off offset:1792 nt
	global_load_dword v129, v103, s[22:23]
	v_mul_lo_u32 v40, v108, s0
	v_add_lshl_u32 v130, v40, v47, 1
	v_add_u32_e32 v40, 0, v130
	s_movk_i32 s3, 0x48
	s_waitcnt vmcnt(17)
	ds_write_b128 v40, v[2:5]
	s_waitcnt vmcnt(16)
	ds_write_b128 v40, v[6:9] offset:17408
	v_mul_lo_u32 v2, v50, s3
	v_mul_lo_u32 v3, v112, s0
	v_add_lshl_u32 v131, v2, v48, 1
	v_add_lshl_u32 v132, v3, v47, 1
	v_add_u32_e32 v2, 0, v131
	v_add_u32_e32 v3, 0, v132
	s_lshl_b32 s0, s9, 8
	v_lshrrev_b32_e32 v40, 1, v46
	s_add_i32 s15, 0, 0x1f100
	v_add_u32_e32 v41, s15, v102
	s_waitcnt vmcnt(15)
	ds_write_b128 v2, v[10:13] offset:44032
	s_waitcnt vmcnt(14)
	ds_write_b128 v3, v[14:17]
	s_waitcnt vmcnt(13)
	ds_write_b128 v3, v[18:21] offset:17408
	v_lshrrev_b32_e32 v3, 3, v49
	v_mul_lo_u32 v3, v3, s3
	v_add_lshl_u32 v133, v3, v48, 1
	v_add_u32_e32 v3, 0, v133
	s_waitcnt vmcnt(12)
	ds_write_b128 v3, v[22:25] offset:44032
	s_waitcnt vmcnt(11)
	ds_write_b128 v2, v[26:29] offset:34816
	v_lshl_add_u64 v[2:3], v[108:109], 0, s[6:7]
	v_lshlrev_b64 v[14:15], 11, v[2:3]
	v_lshl_add_u64 v[2:3], v[104:105], 0, v[14:15]
	v_lshl_add_u64 v[6:7], v[106:107], 0, v[14:15]
	v_lshl_add_u64 v[14:15], v[116:117], 0, v[14:15]
	s_waitcnt lgkmcnt(0)
	s_barrier
	global_load_dwordx4 v[2:5], v[2:3], off nt
	s_nop 0
	global_load_dwordx4 v[6:9], v[6:7], off nt
	v_lshl_add_u64 v[22:23], s[20:21], 0, v[30:31]
	global_load_dwordx4 v[238:241], v[14:15], off nt
	v_lshl_add_u64 v[14:15], v[112:113], 0, s[6:7]
	v_lshlrev_b64 v[26:27], 11, v[14:15]
	v_lshl_add_u64 v[10:11], v[22:23], 0, v[36:37]
	v_lshl_add_u64 v[14:15], v[104:105], 0, v[26:27]
	v_lshl_add_u64 v[18:19], v[106:107], 0, v[26:27]
	v_lshl_add_u64 v[26:27], v[116:117], 0, v[26:27]
	global_load_dwordx4 v[10:13], v[10:11], off nt
	s_nop 0
	global_load_dwordx4 v[14:17], v[14:15], off nt
	s_nop 0
	global_load_dwordx4 v[18:21], v[18:19], off nt
	v_lshl_add_u64 v[22:23], v[22:23], 0, v[42:43]
	global_load_dwordx4 v[246:249], v[26:27], off nt
	v_lshl_add_u64 v[26:27], s[16:17], 0, v[44:45]
	v_lshl_add_u64 v[26:27], v[26:27], 0, v[30:31]
	v_lshl_add_u64 v[28:29], s[18:19], 0, v[34:35]
	global_load_dwordx4 v[22:25], v[22:23], off nt
	v_lshl_add_u64 v[36:37], v[28:29], 0, s[24:25]
	global_load_dwordx4 v[26:29], v[26:27], off nt
	s_nop 0
	global_load_dword v230, v[36:37], off nt
	global_load_dword v231, v[36:37], off offset:256 nt
	global_load_dword v232, v[36:37], off offset:512 nt
	global_load_dword v233, v[36:37], off offset:768 nt
	global_load_dword v234, v[36:37], off offset:1024 nt
	global_load_dword v235, v[36:37], off offset:1280 nt
	global_load_dword v236, v[36:37], off offset:1536 nt
	global_load_dword v237, v[36:37], off offset:1792 nt
	global_load_dword v250, v103, s[4:5]
	s_add_i32 s6, 0, 0x1e800
	s_add_i32 s3, s6, s0
	v_and_b32_e32 v36, 7, v46
	s_lshl_b32 s0, s9, 5
	v_lshlrev_b32_e32 v37, 8, v36
	v_and_or_b32 v40, v40, 28, s0
	v_add3_u32 v136, s6, v37, v40
	v_and_b32_e32 v227, 63, v46
	v_lshl_add_u32 v227, v227, 2, s6
	v_cmp_eq_u32_e64 s[6:7], 0, v36
	s_add_i32 s9, 0, 0x1f000
	v_lshrrev_b32_e32 v36, 2, v46
	s_add_i32 s0, s15, s0
	v_add_u32_e32 v137, s9, v40
	v_and_b32_e32 v134, 12, v36
	v_lshlrev_b32_e32 v228, 2, v134
	v_lshl_add_u32 v40, v1, 1, s0
	s_movk_i32 s0, 0x110
	v_mov_b32_e32 v36, 0x1100
	v_mad_u32_u24 v138, v1, s0, v36
	s_movk_i32 s15, 0x90
	v_mov_b32_e32 v36, 0x900
	v_mad_u32_u24 v140, v1, s15, v36
	v_lshl_add_u32 v141, v134, 2, s9
	v_lshl_add_u64 v[36:37], s[26:27], 0, v[44:45]
	s_add_u32 s9, s94, s12
	v_lshl_add_u64 v[118:119], s[38:39], 0, v[30:31]
	v_lshl_add_u64 v[120:121], v[36:37], 0, v[30:31]
	v_lshl_add_u64 v[122:123], s[66:67], 0, v[34:35]
	s_addc_u32 s13, s95, s13
	v_lshlrev_b64 v[30:31], 12, v[38:39]
	v_lshlrev_b32_e32 v34, 4, v1
	s_add_u32 s12, s9, 0x130008
	v_or3_b32 v30, v30, s28, v34
	s_addc_u32 s13, s13, 0
	s_or_b32 s20, s8, 2
	v_lshl_add_u64 v[30:31], s[94:95], 0, v[30:31]
	s_mov_b64 s[8:9], 0x6b00000
	v_lshl_add_u64 v[124:125], v[30:31], 0, s[8:9]
	v_lshlrev_b64 v[30:31], 12, v[32:33]
	v_or3_b32 v30, v30, s28, v34
	s_mov_b32 s1, 0
	v_and_b32_e32 v135, 48, v46
	v_mul_u32_u24_e32 v42, 0x110, v134
	v_mul_lo_u32 v43, v108, s0
	v_mul_lo_u32 v46, v112, s0
	v_lshl_add_u64 v[30:31], s[94:95], 0, v[30:31]
	v_cmp_eq_u32_e64 s[4:5], 0, v1
	v_mul_u32_u24_e32 v102, 0x110, v1
	v_mul_u32_u24_e32 v139, 0x90, v1
	v_add_u32_e32 v142, 64, v141
	v_add_u32_e32 v143, 0x80, v141
	v_add_u32_e32 v144, 0xc0, v141
	s_mov_b32 s0, s10
	s_bitset1_b32 s14, 7
	v_lshl_add_u64 v[126:127], v[30:31], 0, s[8:9]
	v_mov_b32_e32 v146, 0x358637bd
	v_mov_b32_e32 v148, 0x260
	v_add_u32_e32 v149, v40, v42
	v_add_u32_e32 v150, v41, v43
	v_add_u32_e32 v151, v41, v46
	s_mov_b64 s[16:17], 0x40000
	s_mov_b32 s15, s1
	v_mov_b32_e32 v54, 0
	v_mov_b32_e32 v55, v103
	v_mov_b32_e32 v56, v103
	v_mov_b32_e32 v57, v103
	v_mov_b32_e32 v58, 0
	v_mov_b32_e32 v59, v103
	v_mov_b32_e32 v60, v103
	v_mov_b32_e32 v61, v103
	v_mov_b32_e32 v50, 0
	v_mov_b32_e32 v51, v103
	v_mov_b32_e32 v52, v103
	v_mov_b32_e32 v53, v103
	v_mov_b32_e32 v46, 0
	v_mov_b32_e32 v47, v103
	v_mov_b32_e32 v48, v103
	v_mov_b32_e32 v49, v103
	v_mov_b32_e32 v42, 0
	v_mov_b32_e32 v43, v103
	v_mov_b32_e32 v44, v103
	v_mov_b32_e32 v45, v103
	v_mov_b32_e32 v38, 0
	v_mov_b32_e32 v39, v103
	v_mov_b32_e32 v40, v103
	v_mov_b32_e32 v41, v103
	v_mov_b32_e32 v30, 0
	v_mov_b32_e32 v31, v103
	v_mov_b32_e32 v32, v103
	v_mov_b32_e32 v33, v103
	v_mov_b32_e32 v34, 0
	v_mov_b32_e32 v36, v103
	v_mov_b32_e32 v37, v103
	v_readlane_b32 s41, v245, 27
	v_readlane_b32 s42, v245, 28
	v_readlane_b32 s43, v245, 29
	v_readlane_b32 s44, v245, 30
	v_readlane_b32 s45, v245, 31
	v_readlane_b32 s46, v245, 32
	v_readlane_b32 s47, v245, 33
	v_readlane_b32 s50, v245, 36
	v_readlane_b32 s51, v245, 37
	v_readlane_b32 s52, v245, 38
	v_readlane_b32 s53, v245, 39
	v_readlane_b32 s54, v245, 40
	v_readlane_b32 s55, v245, 41
	s_waitcnt vmcnt(18)
	s_mov_b32 s98, 0xaaaaaaaa
	s_mov_b32 s99, 0xaaaaaaaa
	s_mov_b32 s100, 0xcccccccc
	s_mov_b32 s101, 0xcccccccc
	v_mbcnt_lo_u32_b32 v251, -1, 0
	v_mbcnt_hi_u32_b32 v251, -1, v251
	v_and_b32_e32 v252, 12, v251
	v_lshlrev_b32_e32 v252, 4, v252
	v_and_b32_e32 v251, 3, v251
	v_lshl_add_u32 v251, v251, 2, v252
	v_readfirstlane_b32 s8, v0
	s_nop 3
	s_lshr_b32 s8, s8, 6
	s_cmp_ge_u32 s8, 4
	s_cbranch_scc0 .Lscan_noprio
	s_setprio 1

.LBB0_1041:
	s_bitcmp1_b32 s15, 0
	s_cselect_b32 s8, 0xf400, 0
	s_add_i32 s8, s8, 0
	v_add_u32_e32 v222, s8, v135
	v_add_u32_e32 v87, v222, v102
	ds_read_b128 v[82:85], v87
	ds_read_b128 v[92:95], v87 offset:64
	v_cvt_pk_bf16_f32 v78, v58, v59
	v_cvt_pk_bf16_f32 v79, v60, v61
	v_cvt_pk_bf16_f32 v80, v54, v55
	v_cvt_pk_bf16_f32 v81, v56, v57
	ds_read_b128 v[166:169], v87 offset:128
	ds_read_b128 v[170:173], v87 offset:192
	v_cvt_pk_bf16_f32 v88, v50, v51
	s_waitcnt lgkmcnt(3)
	v_mfma_f32_16x16x32_bf16 v[82:85], v[82:85], v[78:81], 0
	v_cvt_pk_bf16_f32 v89, v52, v53
	v_cvt_pk_bf16_f32 v90, v46, v47
	v_cvt_pk_bf16_f32 v91, v48, v49
	ds_read_b128 v[174:177], v87 offset:4352
	v_cvt_pk_bf16_f32 v96, v42, v43
	s_waitcnt lgkmcnt(3)
	v_mfma_f32_16x16x32_bf16 v[82:85], v[92:95], v[88:91], v[82:85]
	v_cvt_pk_bf16_f32 v97, v44, v45
	v_cvt_pk_bf16_f32 v98, v38, v39
	v_cvt_pk_bf16_f32 v99, v40, v41
	v_cvt_pk_bf16_f32 v92, v30, v31
	v_cvt_pk_bf16_f32 v93, v32, v33
	s_waitcnt lgkmcnt(2)
	v_mfma_f32_16x16x32_bf16 v[82:85], v[166:169], v[96:99], v[82:85]
	ds_read_b128 v[166:169], v87 offset:4416
	v_cvt_pk_bf16_f32 v94, v34, v35
	v_cvt_pk_bf16_f32 v95, v36, v37
	v_add3_u32 v100, s8, v102, v135
	ds_read_b128 v[178:181], v100 offset:8832
	s_waitcnt lgkmcnt(3)
	v_mfma_f32_16x16x32_bf16 v[82:85], v[170:173], v[92:95], v[82:85]
	v_add_u32_e32 v101, v222, v138
	ds_read_b128 v[182:185], v101 offset:8832
	s_waitcnt vmcnt(22)
	v_mov_b32_e32 v223, v152
	s_waitcnt lgkmcnt(3)
	v_mfma_f32_16x16x32_bf16 v[170:173], v[174:177], v[78:81], 0
	ds_read_b128 v[174:177], v87 offset:4480
	s_waitcnt vmcnt(21)
	v_mov_b32_e32 v224, v153
	s_waitcnt vmcnt(20)
	v_mov_b32_e32 v225, v154
	s_waitcnt lgkmcnt(3)
	v_mfma_f32_16x16x32_bf16 v[166:169], v[166:169], v[88:91], v[170:173]
	s_waitcnt vmcnt(19)
	v_mov_b32_e32 v226, v155
	s_nop 0
	ds_read_b128 v[170:173], v87 offset:4544
	s_waitcnt lgkmcnt(1)
	v_mfma_f32_16x16x32_bf16 v[166:169], v[174:177], v[96:99], v[166:169]
	ds_read_b128 v[174:177], v100 offset:8704
	s_waitcnt lgkmcnt(1)
	v_mfma_f32_16x16x32_bf16 v[166:169], v[170:173], v[92:95], v[166:169]
	ds_read_b128 v[170:173], v100 offset:8768
	s_waitcnt lgkmcnt(1)
	v_mfma_f32_16x16x32_bf16 v[174:177], v[174:177], v[78:81], 0
	s_waitcnt lgkmcnt(0)
	v_mfma_f32_16x16x32_bf16 v[170:173], v[170:173], v[88:91], v[174:177]
	s_nop 5
	ds_read_b128 v[174:177], v100 offset:8896
	v_mfma_f32_16x16x32_bf16 v[170:173], v[178:181], v[96:99], v[170:173]
	ds_read_b128 v[178:181], v101 offset:8704
	s_waitcnt lgkmcnt(1)
	v_mfma_f32_16x16x32_bf16 v[170:173], v[174:177], v[92:95], v[170:173]
	ds_read_b128 v[174:177], v101 offset:8768
	s_waitcnt lgkmcnt(1)
	v_mfma_f32_16x16x32_bf16 v[178:181], v[178:181], v[78:81], 0
	s_waitcnt lgkmcnt(0)
	v_mfma_f32_16x16x32_bf16 v[174:177], v[174:177], v[88:91], v[178:181]
	s_nop 5
	ds_read_b128 v[178:181], v101 offset:8896
	v_mfma_f32_16x16x32_bf16 v[174:177], v[182:185], v[96:99], v[174:177]
	ds_read_b128 v[182:185], v87 offset:17408
	ds_read_b128 v[186:189], v87 offset:17472
	ds_read_b128 v[190:193], v87 offset:17600
	ds_read_b128 v[152:155], v87 offset:21824
	s_waitcnt lgkmcnt(3)
	v_mfma_f32_16x16x32_bf16 v[182:185], v[182:185], v[78:81], 0
	v_mfma_f32_16x16x32_bf16 v[174:177], v[178:181], v[92:95], v[174:177]
	ds_read_b128 v[178:181], v87 offset:17536
	s_waitcnt lgkmcnt(3)
	v_mfma_f32_16x16x32_bf16 v[182:185], v[186:189], v[88:91], v[182:185]
	ds_read_b128 v[186:189], v87 offset:21760
	s_waitcnt lgkmcnt(1)
	v_mfma_f32_16x16x32_bf16 v[178:181], v[178:181], v[96:99], v[182:185]
	s_waitcnt lgkmcnt(0)
	v_mfma_f32_16x16x32_bf16 v[186:189], v[186:189], v[78:81], 0
	v_mfma_f32_16x16x32_bf16 v[178:181], v[190:193], v[92:95], v[178:181]
	s_nop 1
	ds_read_b128 v[182:185], v87 offset:21888
	ds_read_b128 v[190:193], v87 offset:21952
	ds_read_b128 v[194:197], v100 offset:26112
	ds_read_b128 v[198:201], v100 offset:26176
	ds_read_b128 v[202:205], v100 offset:26240
	ds_read_b128 v[206:209], v100 offset:26304
	ds_read_b128 v[210:213], v101 offset:26112
	ds_read_b128 v[214:217], v101 offset:26176
	v_lshlrev_b32_e32 v100, 16, v156
	v_mfma_f32_16x16x32_bf16 v[152:155], v[152:155], v[88:91], v[186:189]
	s_nop 2
	ds_read_b128 v[186:189], v101 offset:26240
	ds_read_b128 v[218:221], v101 offset:26304
	v_and_b32_e32 v101, 0xffff0000, v156
	v_pk_add_f32 v[100:101], v[100:101], v[82:83] neg_lo:[0,1] neg_hi:[0,1]
	v_lshlrev_b32_e32 v82, 16, v157
	v_and_b32_e32 v83, 0xffff0000, v157
	v_pk_add_f32 v[156:157], v[82:83], v[84:85] neg_lo:[0,1] neg_hi:[0,1]
	s_waitcnt lgkmcnt(7)
	v_mfma_f32_16x16x32_bf16 v[82:85], v[194:197], v[78:81], 0
	v_add_u32_e32 v194, v222, v139
	v_lshlrev_b32_e32 v87, 16, v225
	v_sub_f32_e32 v87, v87, v174
	s_waitcnt lgkmcnt(3)
	v_mfma_f32_16x16x32_bf16 v[78:81], v[210:213], v[78:81], 0
	v_mfma_f32_16x16x32_bf16 v[152:155], v[182:185], v[96:99], v[152:155]
	v_lshlrev_b32_e32 v182, 16, v145
	v_and_b32_e32 v183, 0xffff0000, v145
	v_pk_add_f32 v[182:183], v[182:183], v[166:167] neg_lo:[0,1] neg_hi:[0,1]
	v_lshlrev_b32_e32 v166, 16, v147
	v_mfma_f32_16x16x32_bf16 v[82:85], v[198:201], v[88:91], v[82:85]
	v_and_b32_e32 v167, 0xffff0000, v147
	v_pk_add_f32 v[184:185], v[166:167], v[168:169] neg_lo:[0,1] neg_hi:[0,1]
	v_lshlrev_b32_e32 v166, 16, v223
	s_waitcnt lgkmcnt(2)
	v_mfma_f32_16x16x32_bf16 v[78:81], v[214:217], v[88:91], v[78:81]
	v_and_b32_e32 v167, 0xffff0000, v223
	v_and_b32_e32 v145, 0xffff0000, v225
	v_lshlrev_b32_e32 v147, 16, v226
	v_mfma_f32_16x16x32_bf16 v[152:155], v[190:193], v[92:95], v[152:155]
	v_add_f32_e64 v190, v166, -v170
	v_add_f32_e64 v191, v167, -v171
	v_lshlrev_b32_e32 v166, 16, v224
	v_and_b32_e32 v167, 0xffff0000, v224
	v_pk_add_f32 v[192:193], v[166:167], v[172:173] neg_lo:[0,1] neg_hi:[0,1]
	ds_read_b128 v[88:91], v194 offset:37120
	ds_read_b128 v[166:169], v194 offset:34816
	v_mfma_f32_16x16x32_bf16 v[82:85], v[202:205], v[96:99], v[82:85]
	v_cvt_pk_bf16_f32 v172, v182, v183
	v_cvt_pk_bf16_f32 v173, v184, v185
	ds_read_b128 v[182:185], v194 offset:39424
	s_waitcnt lgkmcnt(4)
	v_mfma_f32_16x16x32_bf16 v[78:81], v[186:189], v[96:99], v[78:81]
	v_and_b32_e32 v170, 0xffff0000, v226
	v_sub_f32_e32 v177, v170, v177
	v_cvt_pk_bf16_f32 v170, v100, v101
	v_cvt_pk_bf16_f32 v171, v156, v157
	v_mfma_f32_16x16x32_bf16 v[82:85], v[206:209], v[92:95], v[82:85]
	v_cvt_pk_bf16_f32 v174, v190, v191
	s_nop 0
	s_nop 0
	s_nop 0
	s_nop 0
	s_waitcnt lgkmcnt(3)
	v_mfma_f32_16x16x32_bf16 v[78:81], v[218:221], v[92:95], v[78:81]
	v_sub_f32_e32 v92, v147, v176
	v_sub_f32_e32 v93, v145, v175
	v_cvt_pk_bf16_f32 v175, v192, v193
	s_waitcnt lgkmcnt(1)
	v_mfma_f32_16x16x32_bf16 v[98:101], v[166:169], v[170:173], v[178:181]
	ds_read_b128 v[166:169], v194 offset:39488
	v_cvt_pk_bf16_f32 v176, v87, v93
	v_cvt_pk_bf16_f32 v177, v92, v177
	v_mfma_f32_16x16x32_bf16 v[94:97], v[88:91], v[170:173], v[152:155]
	s_nop 0
	s_nop 0
	s_nop 0
	s_nop 0
	ds_read_b128 v[152:155], v194 offset:41728
	s_waitcnt lgkmcnt(2)
	v_mfma_f32_16x16x32_bf16 v[82:85], v[182:185], v[170:173], v[82:85]
	v_mov_b32_e32 v182, v129
	s_nop 0
	s_nop 0
	v_pk_mul_f32 v[60:61], v[60:61], v[182:183] op_sel_hi:[1,0]
	s_waitcnt lgkmcnt(1)
	v_mfma_f32_16x16x32_bf16 v[90:93], v[166:169], v[174:177], v[82:85]
	s_nop 2
	ds_read_b128 v[82:85], v194 offset:41792
	ds_read_b128 v[166:169], v194 offset:44032
	v_pk_mul_f32 v[58:59], v[58:59], v[182:183] op_sel_hi:[1,0]
	v_pk_mul_f32 v[56:57], v[56:57], v[182:183] op_sel_hi:[1,0]
	s_waitcnt lgkmcnt(2)
	v_mfma_f32_16x16x32_bf16 v[78:81], v[152:155], v[170:173], v[78:81]
	ds_read_b128 v[152:155], v194 offset:44096
	v_pk_mul_f32 v[54:55], v[54:55], v[182:183] op_sel_hi:[1,0]
	v_pk_mul_f32 v[52:53], v[52:53], v[182:183] op_sel_hi:[1,0]
	s_waitcnt lgkmcnt(2)
	v_mfma_f32_16x16x32_bf16 v[86:89], v[82:85], v[174:177], v[78:81]
	ds_read_b128 v[82:85], v194 offset:46400
	v_pk_mul_f32 v[50:51], v[50:51], v[182:183] op_sel_hi:[1,0]
	ds_read_b128 v[162:165], v194 offset:51008
	ds_read_b128 v[78:81], v194 offset:46336
	s_waitcnt lgkmcnt(4)
	v_mfma_f32_16x16x32_bf16 v[58:61], v[166:169], v[170:173], v[58:61]
	v_add3_u32 v168, s8, v139, v135
	v_pk_mul_f32 v[48:49], v[48:49], v[182:183] op_sel_hi:[1,0]
	v_pk_mul_f32 v[46:47], v[46:47], v[182:183] op_sel_hi:[1,0]
	s_waitcnt lgkmcnt(3)
	v_mfma_f32_16x16x32_bf16 v[58:61], v[152:155], v[174:177], v[58:61]
	ds_read_b128 v[152:155], v194 offset:48640
	v_add_u32_e32 v166, v222, v140
	v_pk_mul_f32 v[44:45], v[44:45], v[182:183] op_sel_hi:[1,0]
	s_waitcnt lgkmcnt(1)
	v_mfma_f32_16x16x32_bf16 v[54:57], v[78:81], v[170:173], v[54:57]
	ds_read_b128 v[78:81], v194 offset:48704
	v_pk_mul_f32 v[42:43], v[42:43], v[182:183] op_sel_hi:[1,0]
	ds_read_b128 v[178:181], v168 offset:57856
	v_mfma_f32_16x16x32_bf16 v[54:57], v[82:85], v[174:177], v[54:57]
	ds_read_b128 v[82:85], v194 offset:50944
	v_pk_mul_f32 v[40:41], v[40:41], v[182:183] op_sel_hi:[1,0]
	v_pk_mul_f32 v[38:39], v[38:39], v[182:183] op_sel_hi:[1,0]
	s_waitcnt lgkmcnt(3)
	v_mfma_f32_16x16x32_bf16 v[50:53], v[152:155], v[170:173], v[50:53]
	s_nop 0
	s_nop 0
	s_nop 0
	s_waitcnt lgkmcnt(2)
	v_mfma_f32_16x16x32_bf16 v[50:53], v[78:81], v[174:177], v[50:53]
	ds_read_b128 v[78:81], v168 offset:53248
	s_nop 0
	v_pk_mul_f32 v[32:33], v[32:33], v[182:183] op_sel_hi:[1,0]
	s_waitcnt lgkmcnt(1)
	v_mfma_f32_16x16x32_bf16 v[46:49], v[82:85], v[170:173], v[46:49]
	ds_read_b128 v[82:85], v168 offset:53312
	v_pk_mul_f32 v[30:31], v[30:31], v[182:183] op_sel_hi:[1,0]
	v_pk_mul_f32 v[36:37], v[36:37], v[182:183] op_sel_hi:[1,0]
	v_mfma_f32_16x16x32_bf16 v[46:49], v[162:165], v[174:177], v[46:49]
	ds_read_b128 v[160:163], v166 offset:53248
	ds_read_b128 v[164:167], v166 offset:53312
	v_pk_mul_f32 v[34:35], v[34:35], v[182:183] op_sel_hi:[1,0]
	s_waitcnt lgkmcnt(3)
	v_mfma_f32_16x16x32_bf16 v[42:45], v[78:81], v[170:173], v[42:45]
	s_nop 0
	s_nop 0
	ds_read_b128 v[70:73], v168 offset:57920
	s_waitcnt lgkmcnt(3)
	v_mfma_f32_16x16x32_bf16 v[42:45], v[82:85], v[174:177], v[42:45]
	s_nop 0
	s_nop 0
	ds_read_b128 v[74:77], v168 offset:60160
	s_waitcnt lgkmcnt(3)
	v_mfma_f32_16x16x32_bf16 v[38:41], v[160:163], v[170:173], v[38:41]
	ds_read_b128 v[158:161], v168 offset:60224
	v_mfma_f32_16x16x32_bf16 v[30:33], v[178:181], v[170:173], v[30:33]
	s_waitcnt lgkmcnt(1)
	v_mfma_f32_16x16x32_bf16 v[34:37], v[74:77], v[170:173], v[34:37]
	v_mfma_f32_16x16x32_bf16 v[30:33], v[70:73], v[174:177], v[30:33]
	v_mul_f32_e32 v184, v98, v98
	v_mul_f32_e32 v185, v99, v99
	v_mul_f32_e32 v186, v100, v100
	v_mul_f32_e32 v187, v101, v101
	v_mfma_f32_16x16x32_bf16 v[38:41], v[164:167], v[174:177], v[38:41]
	v_mul_f32_e32 v188, v94, v94
	v_mul_f32_e32 v189, v95, v95
	v_mul_f32_e32 v190, v96, v96
	v_mul_f32_e32 v191, v97, v97
	s_waitcnt lgkmcnt(0)
	v_mfma_f32_16x16x32_bf16 v[34:37], v[158:161], v[174:177], v[34:37]
	v_mul_f32_e32 v192, v90, v90
	v_mul_f32_e32 v193, v91, v91
	v_mul_f32_e32 v194, v92, v92
	v_mul_f32_e32 v195, v93, v93
	v_mul_f32_e32 v196, v86, v86
	v_mul_f32_e32 v197, v87, v87
	v_mul_f32_e32 v198, v88, v88
	v_mul_f32_e32 v199, v89, v89
	v_add_f32_dpp v70, v184, v184 row_ror:8 row_mask:0xf bank_mask:0xf
	v_add_f32_dpp v71, v185, v185 row_ror:8 row_mask:0xf bank_mask:0xf
	v_add_f32_dpp v72, v186, v186 row_ror:8 row_mask:0xf bank_mask:0xf
	v_add_f32_dpp v73, v187, v187 row_ror:8 row_mask:0xf bank_mask:0xf
	v_add_f32_dpp v74, v188, v188 row_ror:8 row_mask:0xf bank_mask:0xf
	v_add_f32_dpp v75, v189, v189 row_ror:8 row_mask:0xf bank_mask:0xf
	v_add_f32_dpp v76, v190, v190 row_ror:8 row_mask:0xf bank_mask:0xf
	v_add_f32_dpp v77, v191, v191 row_ror:8 row_mask:0xf bank_mask:0xf
	v_add_f32_dpp v70, v192, v192 row_ror:8 row_mask:0xf bank_mask:0xc
	v_add_f32_dpp v71, v193, v193 row_ror:8 row_mask:0xf bank_mask:0xc
	v_add_f32_dpp v72, v194, v194 row_ror:8 row_mask:0xf bank_mask:0xc
	v_add_f32_dpp v73, v195, v195 row_ror:8 row_mask:0xf bank_mask:0xc
	v_add_f32_dpp v74, v196, v196 row_ror:8 row_mask:0xf bank_mask:0xc
	v_add_f32_dpp v75, v197, v197 row_ror:8 row_mask:0xf bank_mask:0xc
	v_add_f32_dpp v76, v198, v198 row_ror:8 row_mask:0xf bank_mask:0xc
	v_add_f32_dpp v77, v199, v199 row_ror:8 row_mask:0xf bank_mask:0xc
	v_add_f32_dpp v184, v70, v70 row_half_mirror row_mask:0xf bank_mask:0x5
	v_add_f32_dpp v185, v71, v71 row_half_mirror row_mask:0xf bank_mask:0x5
	v_add_f32_dpp v186, v72, v72 row_half_mirror row_mask:0xf bank_mask:0x5
	v_add_f32_dpp v187, v73, v73 row_half_mirror row_mask:0xf bank_mask:0x5
	v_add_f32_dpp v184, v74, v74 row_half_mirror row_mask:0xf bank_mask:0xa
	v_add_f32_dpp v185, v75, v75 row_half_mirror row_mask:0xf bank_mask:0xa
	v_add_f32_dpp v186, v76, v76 row_half_mirror row_mask:0xf bank_mask:0xa
	v_add_f32_dpp v187, v77, v77 row_half_mirror row_mask:0xf bank_mask:0xa
	v_add_f32_dpp v70, v184, v184 quad_perm:[2,3,0,1] row_mask:0xf bank_mask:0xf
	v_add_f32_dpp v71, v186, v186 quad_perm:[2,3,0,1] row_mask:0xf bank_mask:0xf
	v_add_f32_dpp v72, v185, v185 quad_perm:[2,3,0,1] row_mask:0xf bank_mask:0xf
	v_add_f32_dpp v73, v187, v187 quad_perm:[2,3,0,1] row_mask:0xf bank_mask:0xf
	v_cndmask_b32_e64 v74, v70, v71, s[100:101]
	v_cndmask_b32_e64 v75, v72, v73, s[100:101]
	s_nop 0
	v_add_f32_dpp v76, v74, v74 quad_perm:[1,0,3,2] row_mask:0xf bank_mask:0xf
	v_add_f32_dpp v77, v75, v75 quad_perm:[1,0,3,2] row_mask:0xf bank_mask:0xf
	v_add3_u32 v200, s3, v135, v251
	v_cndmask_b32_e64 v76, v76, v77, s[98:99]
	ds_write_b32 v200, v76
	s_waitcnt lgkmcnt(0)
	s_barrier
	ds_read_b32 v70, v227
	ds_read_b32 v71, v227 offset:256
	ds_read_b32 v72, v227 offset:512
	ds_read_b32 v73, v227 offset:768
	ds_read_b32 v74, v227 offset:1024
	ds_read_b32 v75, v227 offset:1280
	ds_read_b32 v76, v227 offset:1536
	ds_read_b32 v77, v227 offset:1792
	s_waitcnt lgkmcnt(0)
	v_add_f32_e32 v70, v70, v71
	v_add_f32_e32 v72, v72, v73
	v_add_f32_e32 v74, v74, v75
	v_add_f32_e32 v76, v76, v77
	v_add_f32_e32 v70, v70, v72
	v_add_f32_e32 v74, v74, v76
	v_add_f32_e32 v70, v70, v74
	v_fmamk_f32 v70, v70, 0x3c000000, v146
	s_mov_b32 s8, 0xf800000
	v_mul_f32_e32 v71, 0x4f800000, v70
	v_cmp_gt_f32_e32 vcc, s8, v70
	s_nop 1
	v_cndmask_b32_e32 v70, v70, v71, vcc
	v_sqrt_f32_e32 v71, v70
	s_nop 0
	v_add_u32_e32 v72, -1, v71
	v_fma_f32 v74, -v72, v71, v70
	v_add_u32_e32 v73, 1, v71
	v_cmp_ge_f32_e64 s[8:9], 0, v74
	s_nop 1
	v_cndmask_b32_e64 v72, v71, v72, s[8:9]
	v_fma_f32 v71, -v73, v71, v70
	v_cmp_lt_f32_e64 s[8:9], 0, v71
	s_nop 1
	v_cndmask_b32_e64 v71, v72, v73, s[8:9]
	v_mul_f32_e32 v72, 0x37800000, v71
	v_cndmask_b32_e32 v71, v71, v72, vcc
	v_cmp_class_f32_e32 vcc, v70, v148
	s_nop 1
	v_cndmask_b32_e32 v70, v71, v70, vcc
	v_div_scale_f32 v71, s[8:9], v70, v70, 1.0
	v_rcp_f32_e32 v72, v71
	s_nop 0
	v_fma_f32 v73, -v71, v72, 1.0
	v_fmac_f32_e32 v72, v73, v72
	v_div_scale_f32 v73, vcc, 1.0, v70, 1.0
	v_mul_f32_e32 v74, v73, v72
	v_fma_f32 v75, -v71, v74, v73
	v_fmac_f32_e32 v74, v75, v72
	v_fma_f32 v71, -v71, v74, v73
	v_div_fmas_f32 v71, v71, v72, v74
	v_div_fixup_f32 v229, v71, v70, 1.0
.LBB0_1075:
	s_add_i32 s8, s15, 1
	s_cmp_eq_u32 s15, 31
	s_cbranch_scc1 .LBB0_1077
	s_bitcmp1_b32 s8, 0
	s_cselect_b32 s9, 0xf400, 0
	s_add_i32 s9, s9, 0
	v_add_u32_e32 v70, s9, v130
	s_waitcnt vmcnt(9)
	ds_write_b128 v70, v[2:5]
	ds_write_b128 v70, v[6:9] offset:17408
	v_add_u32_e32 v70, s9, v131
	v_add_u32_e32 v71, s9, v132
	ds_write_b128 v70, v[10:13] offset:44032
	ds_write_b128 v71, v[14:17]
	ds_write_b128 v71, v[18:21] offset:17408
	v_add_u32_e32 v71, s9, v133
	ds_write_b128 v71, v[22:25] offset:44032
	ds_write_b128 v70, v[26:29] offset:34816
.LBB0_1077:
	s_waitcnt lgkmcnt(0)
	s_nop 0
	ds_bpermute_b32 v70, v228, v229 offset:0
	ds_bpermute_b32 v71, v228, v229 offset:4
	ds_bpermute_b32 v72, v228, v229 offset:8
	ds_bpermute_b32 v73, v228, v229 offset:12
	ds_bpermute_b32 v74, v228, v229 offset:64
	ds_bpermute_b32 v75, v228, v229 offset:68
	ds_bpermute_b32 v76, v228, v229 offset:72
	ds_bpermute_b32 v77, v228, v229 offset:76
	s_cmp_gt_u32 s15, 29
	s_nop 0
	s_nop 0
	s_waitcnt lgkmcnt(4)
	v_mul_f32_e32 v70, v98, v70
	v_mul_f32_e32 v70, v128, v70
	v_mul_f32_e32 v71, v99, v71
	v_cvt_pk_bf16_f32 v70, v70, s0
	ds_write_b16 v149, v70
	v_mul_f32_e32 v70, v128, v71
	v_cvt_pk_bf16_f32 v70, v70, s0
	ds_write_b16 v149, v70 offset:272
	v_mul_f32_e32 v70, v100, v72
	v_mul_f32_e32 v70, v128, v70
	v_cvt_pk_bf16_f32 v70, v70, s0
	ds_write_b16 v149, v70 offset:544
	v_mul_f32_e32 v70, v101, v73
	v_mul_f32_e32 v70, v128, v70
	v_cvt_pk_bf16_f32 v70, v70, s0
	ds_write_b16 v149, v70 offset:816
	s_waitcnt lgkmcnt(4)
	v_mul_f32_e32 v70, v94, v74
	v_mul_f32_e32 v70, v128, v70
	v_cvt_pk_bf16_f32 v70, v70, s0
	ds_write_b16 v149, v70 offset:4352
	v_mul_f32_e32 v70, v95, v75
	v_mul_f32_e32 v70, v128, v70
	v_cvt_pk_bf16_f32 v70, v70, s0
	ds_write_b16 v149, v70 offset:4624
	v_mul_f32_e32 v70, v96, v76
	v_mul_f32_e32 v70, v128, v70
	v_cvt_pk_bf16_f32 v70, v70, s0
	ds_write_b16 v149, v70 offset:4896
	ds_bpermute_b32 v70, v228, v229 offset:128
	ds_bpermute_b32 v71, v228, v229 offset:132
	ds_bpermute_b32 v72, v228, v229 offset:136
	ds_bpermute_b32 v73, v228, v229 offset:140
	v_mul_f32_e32 v74, v97, v77
	v_mul_f32_e32 v74, v128, v74
	v_cvt_pk_bf16_f32 v74, v74, s0
	ds_write_b16 v149, v74 offset:5168
	ds_bpermute_b32 v74, v228, v229 offset:192
	ds_bpermute_b32 v75, v228, v229 offset:196
	ds_bpermute_b32 v76, v228, v229 offset:200
	ds_bpermute_b32 v77, v228, v229 offset:204
	s_waitcnt lgkmcnt(5)
	v_mul_f32_e32 v70, v90, v70
	v_mul_f32_e32 v70, v128, v70
	v_cvt_pk_bf16_f32 v70, v70, s0
	ds_write_b16 v149, v70 offset:8704
	v_mul_f32_e32 v70, v91, v71
	v_mul_f32_e32 v70, v128, v70
	v_cvt_pk_bf16_f32 v70, v70, s0
	ds_write_b16 v149, v70 offset:8976
	v_mul_f32_e32 v70, v92, v72
	v_mul_f32_e32 v70, v128, v70
	v_cvt_pk_bf16_f32 v70, v70, s0
	ds_write_b16 v149, v70 offset:9248
	v_mul_f32_e32 v70, v93, v73
	v_mul_f32_e32 v70, v128, v70
	v_cvt_pk_bf16_f32 v70, v70, s0
	ds_write_b16 v149, v70 offset:9520
	s_waitcnt lgkmcnt(4)
	v_mul_f32_e32 v70, v86, v74
	v_mul_f32_e32 v70, v128, v70
	v_cvt_pk_bf16_f32 v70, v70, s0
	ds_write_b16 v149, v70 offset:13056
	v_mul_f32_e32 v70, v87, v75
	v_mul_f32_e32 v70, v128, v70
	v_cvt_pk_bf16_f32 v70, v70, s0
	ds_write_b16 v149, v70 offset:13328
	v_mul_f32_e32 v70, v88, v76
	v_mul_f32_e32 v70, v128, v70
	v_cvt_pk_bf16_f32 v70, v70, s0
	ds_write_b16 v149, v70 offset:13600
	v_mul_f32_e32 v70, v89, v77
	v_mul_f32_e32 v70, v128, v70
	v_cvt_pk_bf16_f32 v70, v70, s0
	ds_write_b16 v149, v70 offset:13872
	s_waitcnt lgkmcnt(0)
	s_barrier
	ds_read_b128 v[70:73], v150
	ds_read_b128 v[74:77], v151
	v_lshlrev_b32_e32 v88, 16, v66
	v_and_b32_e32 v89, 0xffff0000, v66
	s_nop 0
	s_waitcnt lgkmcnt(1)
	v_lshlrev_b32_e32 v86, 16, v70
	v_and_b32_e32 v87, 0xffff0000, v70
	v_pk_mul_f32 v[86:87], v[88:89], v[86:87]
	v_lshlrev_b32_e32 v70, 16, v71
	v_cvt_pk_bf16_f32 v66, v86, v87
	v_and_b32_e32 v71, 0xffff0000, v71
	v_lshlrev_b32_e32 v86, 16, v67
	v_and_b32_e32 v87, 0xffff0000, v67
	v_pk_mul_f32 v[70:71], v[86:87], v[70:71]
	v_lshlrev_b32_e32 v86, 16, v68
	v_cvt_pk_bf16_f32 v67, v70, v71
	v_lshlrev_b32_e32 v70, 16, v72
	v_and_b32_e32 v71, 0xffff0000, v72
	v_and_b32_e32 v87, 0xffff0000, v68
	v_pk_mul_f32 v[70:71], v[86:87], v[70:71]
	v_lshlrev_b32_e32 v72, 16, v69
	v_cvt_pk_bf16_f32 v68, v70, v71
	v_lshlrev_b32_e32 v70, 16, v73
	v_and_b32_e32 v71, 0xffff0000, v73
	v_and_b32_e32 v73, 0xffff0000, v69
	v_pk_mul_f32 v[70:71], v[72:73], v[70:71]
	s_nop 0
	v_cvt_pk_bf16_f32 v69, v70, v71
	global_store_dwordx4 v[126:127], v[66:69], off
	s_nop 0
	s_nop 0
	s_waitcnt lgkmcnt(0)
	v_lshlrev_b32_e32 v66, 16, v74
	v_and_b32_e32 v67, 0xffff0000, v74
	v_lshlrev_b32_e32 v68, 16, v62
	v_and_b32_e32 v69, 0xffff0000, v62
	v_pk_mul_f32 v[66:67], v[68:69], v[66:67]
	v_lshlrev_b32_e32 v68, 16, v63
	v_cvt_pk_bf16_f32 v62, v66, v67
	v_lshlrev_b32_e32 v66, 16, v75
	v_and_b32_e32 v67, 0xffff0000, v75
	v_and_b32_e32 v69, 0xffff0000, v63
	v_pk_mul_f32 v[66:67], v[68:69], v[66:67]
	v_lshlrev_b32_e32 v68, 16, v64
	v_cvt_pk_bf16_f32 v63, v66, v67
	v_lshlrev_b32_e32 v66, 16, v76
	v_and_b32_e32 v67, 0xffff0000, v76
	v_and_b32_e32 v69, 0xffff0000, v64
	v_pk_mul_f32 v[66:67], v[68:69], v[66:67]
	v_lshlrev_b32_e32 v68, 16, v65
	v_cvt_pk_bf16_f32 v64, v66, v67
	v_lshlrev_b32_e32 v66, 16, v77
	v_and_b32_e32 v67, 0xffff0000, v77
	v_and_b32_e32 v69, 0xffff0000, v65
	v_pk_mul_f32 v[66:67], v[68:69], v[66:67]
	s_nop 0
	v_cvt_pk_bf16_f32 v65, v66, v67
	s_nop 0
	s_nop 0
	s_nop 0
	s_nop 0
	s_nop 0
	s_nop 0
	global_store_dwordx4 v[124:125], v[62:65], off
	s_waitcnt vmcnt(2)
	v_mov_b32_e32 v129, v250
	v_mov_b32_e32 v156, v230
	v_mov_b32_e32 v157, v231
	v_mov_b32_e32 v145, v232
	v_mov_b32_e32 v147, v233
	v_mov_b32_e32 v152, v234
	v_mov_b32_e32 v153, v235
	v_mov_b32_e32 v154, v236
	v_mov_b32_e32 v155, v237
	v_mov_b64_e32 v[78:79], v[238:239]
	v_mov_b64_e32 v[80:81], v[240:241]
	v_mov_b64_e32 v[82:83], v[246:247]
	v_mov_b64_e32 v[84:85], v[248:249]
	s_cbranch_scc1 .LBB0_1040
	s_add_i32 s18, s20, s15
	s_ashr_i32 s15, s14, 31
	v_lshl_add_u64 v[2:3], s[14:15], 0, v[108:109]
	v_lshlrev_b64 v[14:15], 11, v[2:3]
	v_lshl_add_u64 v[2:3], v[104:105], 0, v[14:15]
	v_lshl_add_u64 v[6:7], v[106:107], 0, v[14:15]
	v_lshl_add_u64 v[14:15], v[116:117], 0, v[14:15]
	s_ashr_i32 s19, s18, 31
	global_load_dwordx4 v[238:241], v[14:15], off nt
	v_lshl_add_u64 v[14:15], s[14:15], 0, v[112:113]
	s_lshl_b64 s[22:23], s[18:19], 14
	v_lshlrev_b64 v[26:27], 11, v[14:15]
	v_lshl_add_u64 v[22:23], v[118:119], 0, s[22:23]
	v_lshl_add_u64 v[14:15], v[104:105], 0, v[26:27]
	v_lshl_add_u64 v[18:19], v[106:107], 0, v[26:27]
	v_lshl_add_u64 v[26:27], v[116:117], 0, v[26:27]
	s_lshl_b64 s[18:19], s[18:19], 13
	v_lshl_add_u64 v[62:63], v[122:123], 0, s[22:23]
	v_lshl_add_u64 v[10:11], v[110:111], 1, v[22:23]
	v_lshl_add_u64 v[22:23], v[114:115], 1, v[22:23]
	global_load_dwordx4 v[246:249], v[26:27], off nt
	v_lshl_add_u64 v[26:27], v[120:121], 0, s[18:19]
	v_lshl_add_u64 v[64:65], s[0:1], 2, v[62:63]
	v_lshl_add_u64 v[62:63], s[10:11], 2, v[62:63]
	global_load_dwordx4 v[2:5], v[2:3], off nt
	s_nop 0
	global_load_dwordx4 v[6:9], v[6:7], off nt
	s_nop 0
	global_load_dwordx4 v[10:13], v[10:11], off nt
	s_nop 0
	global_load_dwordx4 v[14:17], v[14:15], off nt
	s_nop 0
	global_load_dwordx4 v[18:21], v[18:19], off nt
	s_nop 0
	global_load_dwordx4 v[22:25], v[22:23], off nt
	s_nop 0
	global_load_dwordx4 v[26:29], v[26:27], off nt
	s_nop 0
	global_load_dword v230, v[64:65], off nt
	global_load_dword v231, v[62:63], off offset:256 nt
	global_load_dword v232, v[62:63], off offset:512 nt
	global_load_dword v233, v[62:63], off offset:768 nt
	global_load_dword v234, v[62:63], off offset:1024 nt
	global_load_dword v235, v[62:63], off offset:1280 nt
	global_load_dword v236, v[62:63], off offset:1536 nt
	global_load_dword v237, v[62:63], off offset:1792 nt
	global_load_dword v250, v103, s[12:13]
	s_branch .LBB0_1040
